# v3 + shorter grid barrier (poll TOP directly) + attention output stores widened to dwordx4 via v_permlane16_swap
# speedup vs baseline: 1.0103x; 1.0103x over previous
; __device__ __forceinline__ void attn_phase(int wv, const Args& a, LAS unsigned char* lds, int w, bool dmy) {
;     ...
;         bf16x8 qc[4];
; #pragma unroll
;         for (int k4 = 0; k4 < 4; ++k4) qc[k4] = qf[k4];
;     ...
;         if (fq == 0) (dmy ? (float*)(a.ws + WS_DUMMY + MiB) + qi * 12 : LSE + tokq * 12)[head] = mx + __logf(sum);
;         __syncthreads();
;     }
.LBB0_652:
	s_or_b64 exec, exec, s[86:87]
	s_add_i32 s4, s4, 1
	s_waitcnt vmcnt(5)
	v_mov_b64_e32 v[50:51], v[46:47]
	v_mov_b64_e32 v[54:55], v[42:43]
	v_mov_b64_e32 v[58:59], v[38:39]
	v_mov_b64_e32 v[62:63], v[34:35]
	s_cmp_lg_u32 s4, 12
	v_mov_b64_e32 v[48:49], v[44:45]
	v_mov_b64_e32 v[52:53], v[40:41]
	v_mov_b64_e32 v[56:57], v[36:37]
	v_mov_b64_e32 v[60:61], v[32:33]
	s_mov_b64 s[86:87], s[84:85]
	s_mov_b32 s80, s82
	s_mov_b32 s1, s83
	s_mov_b32 s0, s5
	s_mov_b32 s81, s8
	s_mov_b32 s82, 0x40000
	s_mov_b32 s83, 0x18000
	s_mov_b32 s84, 0x10000
	s_mov_b32 s85, 0x8000
	s_mov_b32 s88, 0x48000
	s_mov_b32 s89, 0x50000
	s_mov_b64 s[90:91], 0x58000
	s_barrier
	s_cbranch_scc0 .LBB0_659

; __device__ __forceinline__ unsigned pk2(float lo, float hi) { f32x2 v = {lo, hi}; bf2_t b = __builtin_convertvector(v, bf2_t); return __builtin_bit_cast(unsigned, b); }
; __device__ __forceinline__ float shx(float v, int lane, int mask) { return __int_as_float(__builtin_amdgcn_ds_bpermute((lane ^ mask) << 2, __float_as_int(v))); }
; __device__ __forceinline__ void attn_phase(int wv, const Args& a, LAS unsigned char* lds, int w, bool dmy) {
;     ...
;         mx = fmaxf(mx, shx(mx, LANE_, 16)); mx = fmaxf(mx, shx(mx, LANE_, 32));
;         float sum = 0.f;
; #pragma unroll
;         for (int i = 0; i < 10; ++i)
; #pragma unroll
;             for (int rr = 0; rr < 4; ++rr) { const float pv = __expf(sT[i][rr] - mx); sT[i][rr] = pv; sum += pv; }
;         sum += shx(sum, LANE_, 16); sum += shx(sum, LANE_, 32);
;         f32x4 oacc[8];
; #pragma unroll
;         for (int j = 0; j < 8; ++j) oacc[j] = (f32x4){0.f, 0.f, 0.f, 0.f};
; #pragma unroll
;         for (int pp = 0; pp < 5; ++pp) {
;             const int pk0 = (lo2 + 2 * pp) ^ px, pk1 = (lo2 + 2 * pp + 1) ^ px;
;             u32x4 pw; pw.x = pk2(sT[2 * pp][0], sT[2 * pp][1]); pw.y = pk2(sT[2 * pp][2], sT[2 * pp][3]); pw.z = pk2(sT[2 * pp + 1][0], sT[2 * pp + 1][1]); pw.w = pk2(sT[2 * pp + 1][2], sT[2 * pp + 1][3]);
.Lat_n_ok:
	v_max3_f32 v65, v124, v125, v126
	v_max3_f32 v65, v65, v127, v128
	v_max3_f32 v65, v65, v129, v130
	v_max3_f32 v65, v65, v131, v132
	v_max3_f32 v65, v65, v133, v134
	v_max3_f32 v65, v65, v135, v136
	v_max3_f32 v65, v65, v137, v138
	v_max3_f32 v65, v65, v139, v140
	v_max3_f32 v65, v65, v141, v142
	v_max3_f32 v65, v65, v143, v144
	v_max3_f32 v65, v65, v145, v146
	v_max3_f32 v65, v65, v147, v148
	v_max3_f32 v65, v65, v149, v150
	v_max3_f32 v65, v65, v151, v152
	v_max3_f32 v65, v65, v153, v154
	v_max3_f32 v65, v65, v155, v156
	v_max3_f32 v65, v65, v157, v158
	v_max_f32_e32 v65, v65, v159
	ds_bpermute_b32 v67, v97, v65
	s_waitcnt lgkmcnt(0)
	v_max_f32_e32 v65, v65, v67
	ds_bpermute_b32 v67, v104, v65
	s_waitcnt lgkmcnt(0)
	v_max_f32_e32 v65, v65, v67
	v_mul_f32_e32 v101, v65, v66
	v_mul_f32_e32 v65, v65, v64
	v_fma_f32 v124, v124, v64, -v65
	v_fma_f32 v125, v125, v64, -v65
	v_fma_f32 v126, v126, v64, -v65
	v_fma_f32 v127, v127, v64, -v65
	v_fma_f32 v128, v128, v64, -v65
	v_fma_f32 v129, v129, v64, -v65
	v_fma_f32 v130, v130, v64, -v65
	v_fma_f32 v131, v131, v64, -v65
	v_fma_f32 v132, v132, v64, -v65
	v_fma_f32 v133, v133, v64, -v65
	v_fma_f32 v134, v134, v64, -v65
	v_fma_f32 v135, v135, v64, -v65
	v_fma_f32 v136, v136, v64, -v65
	v_fma_f32 v137, v137, v64, -v65
	v_fma_f32 v138, v138, v64, -v65
	v_fma_f32 v139, v139, v64, -v65
	v_fma_f32 v140, v140, v64, -v65
	v_fma_f32 v141, v141, v64, -v65
	v_fma_f32 v142, v142, v64, -v65
	v_fma_f32 v143, v143, v64, -v65
	v_fma_f32 v144, v144, v64, -v65
	v_fma_f32 v145, v145, v64, -v65
	v_fma_f32 v146, v146, v64, -v65
	v_fma_f32 v147, v147, v64, -v65
	v_fma_f32 v148, v148, v64, -v65
	v_fma_f32 v149, v149, v64, -v65
	v_fma_f32 v150, v150, v64, -v65
	v_fma_f32 v151, v151, v64, -v65
	v_fma_f32 v152, v152, v64, -v65
	v_fma_f32 v153, v153, v64, -v65
	v_fma_f32 v154, v154, v64, -v65
	v_fma_f32 v155, v155, v64, -v65
	v_fma_f32 v156, v156, v64, -v65
	v_fma_f32 v157, v157, v64, -v65
	v_fma_f32 v158, v158, v64, -v65
	v_fma_f32 v159, v159, v64, -v65
	v_exp_f32_e32 v124, v124
	v_exp_f32_e32 v125, v125
	v_exp_f32_e32 v126, v126
	v_add_f32_e32 v103, v124, v125
	v_exp_f32_e32 v127, v127
	v_add_f32_e32 v103, v103, v126
	v_exp_f32_e32 v128, v128
	v_add_f32_e32 v103, v103, v127
	v_exp_f32_e32 v129, v129
	v_add_f32_e32 v103, v103, v128
	v_exp_f32_e32 v130, v130
	v_add_f32_e32 v103, v103, v129
	v_exp_f32_e32 v131, v131
	v_add_f32_e32 v103, v103, v130
	v_exp_f32_e32 v132, v132
	v_add_f32_e32 v103, v103, v131
	v_exp_f32_e32 v133, v133
	v_add_f32_e32 v103, v103, v132
	v_exp_f32_e32 v134, v134
	v_add_f32_e32 v103, v103, v133
	v_exp_f32_e32 v135, v135
	v_add_f32_e32 v103, v103, v134
	v_exp_f32_e32 v136, v136
	v_add_f32_e32 v103, v103, v135
	v_exp_f32_e32 v137, v137
	v_add_f32_e32 v103, v103, v136
	v_exp_f32_e32 v138, v138
	v_add_f32_e32 v103, v103, v137
	v_exp_f32_e32 v139, v139
	v_add_f32_e32 v103, v103, v138
	v_exp_f32_e32 v140, v140
	v_add_f32_e32 v103, v103, v139
	v_exp_f32_e32 v141, v141
	v_add_f32_e32 v103, v103, v140
	v_exp_f32_e32 v142, v142
	v_add_f32_e32 v103, v103, v141
	v_exp_f32_e32 v143, v143
	v_add_f32_e32 v103, v103, v142
	v_exp_f32_e32 v144, v144
	v_add_f32_e32 v103, v103, v143
	v_exp_f32_e32 v145, v145
	v_add_f32_e32 v103, v103, v144
	v_exp_f32_e32 v146, v146
	v_add_f32_e32 v103, v103, v145
	v_exp_f32_e32 v147, v147
	v_add_f32_e32 v103, v103, v146
	v_exp_f32_e32 v148, v148
	v_add_f32_e32 v103, v103, v147
	v_exp_f32_e32 v149, v149
	v_add_f32_e32 v103, v103, v148
	v_exp_f32_e32 v150, v150
	v_add_f32_e32 v103, v103, v149
	v_exp_f32_e32 v151, v151
	v_add_f32_e32 v103, v103, v150
	v_exp_f32_e32 v152, v152
	v_add_f32_e32 v103, v103, v151
	v_exp_f32_e32 v153, v153
	v_add_f32_e32 v103, v103, v152
	v_exp_f32_e32 v154, v154
	v_add_f32_e32 v103, v103, v153
	v_exp_f32_e32 v155, v155
	v_add_f32_e32 v103, v103, v154
	v_exp_f32_e32 v156, v156
	v_add_f32_e32 v103, v103, v155
	v_exp_f32_e32 v157, v157
	v_add_f32_e32 v103, v103, v156
	v_exp_f32_e32 v158, v158
	v_add_f32_e32 v103, v103, v157
	v_exp_f32_e32 v159, v159
	v_add_f32_e32 v103, v103, v158
	s_nop 0
	v_add_f32_e32 v103, v103, v159
	ds_bpermute_b32 v67, v97, v103
	v_cvt_pk_bf16_f32 v166, v124, v125
	v_cvt_pk_bf16_f32 v167, v126, v127
	v_cvt_pk_bf16_f32 v168, v128, v129
	v_cvt_pk_bf16_f32 v169, v130, v131
	v_cvt_pk_bf16_f32 v170, v132, v133
	v_cvt_pk_bf16_f32 v171, v134, v135
	v_cvt_pk_bf16_f32 v172, v136, v137
	v_cvt_pk_bf16_f32 v173, v138, v139
	v_cvt_pk_bf16_f32 v174, v140, v141
	v_cvt_pk_bf16_f32 v175, v142, v143
	v_cvt_pk_bf16_f32 v176, v144, v145
	v_cvt_pk_bf16_f32 v177, v146, v147
	v_cvt_pk_bf16_f32 v178, v148, v149
	v_cvt_pk_bf16_f32 v179, v150, v151
	v_cvt_pk_bf16_f32 v180, v152, v153
	v_cvt_pk_bf16_f32 v181, v154, v155
	v_cvt_pk_bf16_f32 v198, v156, v157
	v_cvt_pk_bf16_f32 v199, v158, v159
	v_mov_b32_e32 v200, 0
	v_mov_b32_e32 v201, 0
	s_waitcnt lgkmcnt(0)
	v_add_f32_e32 v103, v103, v67
	ds_bpermute_b32 v67, v104, v103
	s_waitcnt lgkmcnt(0)
	v_add_f32_e32 v81, v103, v67
	ds_read_b64 v[48:49], v182
	ds_read_b64 v[50:51], v183
	ds_read_b64 v[52:53], v182 offset:8448
	ds_read_b64 v[54:55], v183 offset:8448
	ds_read_b64 v[56:57], v182 offset:16896
	ds_read_b64 v[58:59], v183 offset:16896
	ds_read_b64 v[60:61], v182 offset:25344
	ds_read_b64 v[62:63], v183 offset:25344
	ds_read_b64 v[64:65], v182 offset:33792
	ds_read_b64 v[66:67], v183 offset:33792
	ds_read_b64 v[68:69], v182 offset:42240
	ds_read_b64 v[70:71], v183 offset:42240
	ds_read_b64 v[72:73], v182 offset:50688
	ds_read_b64 v[74:75], v183 offset:50688
	ds_read_b64 v[76:77], v182 offset:59136
	s_waitcnt lgkmcnt(14)
	ds_read_b64 v[78:79], v183 offset:59136
	s_waitcnt lgkmcnt(8)
; #define LAS __attribute__((address_space(3)))
; __device__ __forceinline__ unsigned pk2(float lo, float hi) { f32x2 v = {lo, hi}; bf2_t b = __builtin_convertvector(v, bf2_t); return __builtin_bit_cast(unsigned, b); }
; __device__ __forceinline__ f32x4 mfma16(bf16x8 a, bf16x8 b, f32x4 c) { return __builtin_amdgcn_mfma_f32_16x16x32_bf16(a, b, c, 0, 0, 0); }
; __device__ __forceinline__ void attn_phase(int wv, const Args& a, LAS unsigned char* lds, int w, bool dmy) {
;     ...
; #pragma unroll
;         for (int pp = 0; pp < 5; ++pp) {
;             const int pk0 = (lo2 + 2 * pp) ^ px, pk1 = (lo2 + 2 * pp + 1) ^ px;
;             u32x4 pw; pw.x = pk2(sT[2 * pp][0], sT[2 * pp][1]); pw.y = pk2(sT[2 * pp][2], sT[2 * pp][3]); pw.z = pk2(sT[2 * pp + 1][0], sT[2 * pp + 1][1]); pw.w = pk2(sT[2 * pp + 1][2], sT[2 * pp + 1][3]);
;             const bf16x8 pf = __builtin_bit_cast(bf16x8, pw);
; #pragma unroll
;             for (int j = 0; j < 8; ++j) {
;                 const u32x2 v0 = *(const LAS u32x2*)(lds + AT_V + ((j * 16 + fr) * 264 + pk0 * 16 + 4 * fq) * 2);
;                 const u32x2 v1 = *(const LAS u32x2*)(lds + AT_V + ((j * 16 + fr) * 264 + pk1 * 16 + 4 * fq) * 2);
;                 const u32x4 vw = (u32x4){v0.x, v0.y, v1.x, v1.y};
;                 oacc[j] = mfma16(__builtin_bit_cast(bf16x8, vw), pf, oacc[j]);
;             }
;         }
	v_mfma_f32_16x16x32_bf16 v[124:127], v[48:51], v[166:169], 0
	v_mfma_f32_16x16x32_bf16 v[128:131], v[52:55], v[166:169], 0
	v_mfma_f32_16x16x32_bf16 v[132:135], v[56:59], v[166:169], 0
	v_mfma_f32_16x16x32_bf16 v[136:139], v[60:63], v[166:169], 0
	ds_read_b64 v[48:49], v184
	ds_read_b64 v[50:51], v185
	ds_read_b64 v[52:53], v184 offset:8448
	ds_read_b64 v[54:55], v185 offset:8448
	ds_read_b64 v[56:57], v184 offset:16896
	ds_read_b64 v[58:59], v185 offset:16896
	ds_read_b64 v[60:61], v184 offset:25344
	s_waitcnt lgkmcnt(14)
	ds_read_b64 v[62:63], v185 offset:25344
	s_waitcnt lgkmcnt(8)
	v_mfma_f32_16x16x32_bf16 v[140:143], v[64:67], v[166:169], 0
	v_mfma_f32_16x16x32_bf16 v[144:147], v[68:71], v[166:169], 0
	v_mfma_f32_16x16x32_bf16 v[148:151], v[72:75], v[166:169], 0
	v_mfma_f32_16x16x32_bf16 v[152:155], v[76:79], v[166:169], 0
	ds_read_b64 v[64:65], v184 offset:33792
	ds_read_b64 v[66:67], v185 offset:33792
	ds_read_b64 v[68:69], v184 offset:42240
	ds_read_b64 v[70:71], v185 offset:42240
	ds_read_b64 v[72:73], v184 offset:50688
	ds_read_b64 v[74:75], v185 offset:50688
	ds_read_b64 v[76:77], v184 offset:59136
	s_waitcnt lgkmcnt(14)
	ds_read_b64 v[78:79], v185 offset:59136
	s_waitcnt lgkmcnt(8)
	v_mfma_f32_16x16x32_bf16 v[124:127], v[48:51], v[170:173], v[124:127]
	v_mfma_f32_16x16x32_bf16 v[128:131], v[52:55], v[170:173], v[128:131]
	v_mfma_f32_16x16x32_bf16 v[132:135], v[56:59], v[170:173], v[132:135]
	v_mfma_f32_16x16x32_bf16 v[136:139], v[60:63], v[170:173], v[136:139]
	ds_read_b64 v[48:49], v186
	ds_read_b64 v[50:51], v187
	ds_read_b64 v[52:53], v186 offset:8448
	ds_read_b64 v[54:55], v187 offset:8448
	ds_read_b64 v[56:57], v186 offset:16896
	ds_read_b64 v[58:59], v187 offset:16896
	ds_read_b64 v[60:61], v186 offset:25344
	s_waitcnt lgkmcnt(14)
	ds_read_b64 v[62:63], v187 offset:25344
	s_waitcnt lgkmcnt(8)
	v_mfma_f32_16x16x32_bf16 v[140:143], v[64:67], v[170:173], v[140:143]
	v_mfma_f32_16x16x32_bf16 v[144:147], v[68:71], v[170:173], v[144:147]
	v_mfma_f32_16x16x32_bf16 v[148:151], v[72:75], v[170:173], v[148:151]
	v_mfma_f32_16x16x32_bf16 v[152:155], v[76:79], v[170:173], v[152:155]
	ds_read_b64 v[64:65], v186 offset:33792
	ds_read_b64 v[66:67], v187 offset:33792
	ds_read_b64 v[68:69], v186 offset:42240
	ds_read_b64 v[70:71], v187 offset:42240
	ds_read_b64 v[72:73], v186 offset:50688
	ds_read_b64 v[74:75], v187 offset:50688
	ds_read_b64 v[76:77], v186 offset:59136
	s_waitcnt lgkmcnt(14)
	ds_read_b64 v[78:79], v187 offset:59136
	s_waitcnt lgkmcnt(8)
	v_mfma_f32_16x16x32_bf16 v[124:127], v[48:51], v[174:177], v[124:127]
	v_mfma_f32_16x16x32_bf16 v[128:131], v[52:55], v[174:177], v[128:131]
	v_mfma_f32_16x16x32_bf16 v[132:135], v[56:59], v[174:177], v[132:135]
	v_mfma_f32_16x16x32_bf16 v[136:139], v[60:63], v[174:177], v[136:139]
	ds_read_b64 v[48:49], v227
	ds_read_b64 v[50:51], v228
	ds_read_b64 v[52:53], v227 offset:8448
	ds_read_b64 v[54:55], v228 offset:8448
	ds_read_b64 v[56:57], v227 offset:16896
	ds_read_b64 v[58:59], v228 offset:16896
	ds_read_b64 v[60:61], v227 offset:25344
	s_waitcnt lgkmcnt(14)
	ds_read_b64 v[62:63], v228 offset:25344
	s_waitcnt lgkmcnt(8)
	v_mfma_f32_16x16x32_bf16 v[140:143], v[64:67], v[174:177], v[140:143]
	v_mfma_f32_16x16x32_bf16 v[144:147], v[68:71], v[174:177], v[144:147]
	v_mfma_f32_16x16x32_bf16 v[148:151], v[72:75], v[174:177], v[148:151]
	v_mfma_f32_16x16x32_bf16 v[152:155], v[76:79], v[174:177], v[152:155]
	ds_read_b64 v[64:65], v227 offset:33792
	ds_read_b64 v[66:67], v228 offset:33792
	ds_read_b64 v[68:69], v227 offset:42240
	ds_read_b64 v[70:71], v228 offset:42240
	ds_read_b64 v[72:73], v227 offset:50688
	ds_read_b64 v[74:75], v228 offset:50688
	ds_read_b64 v[76:77], v227 offset:59136
	s_waitcnt lgkmcnt(14)
	ds_read_b64 v[78:79], v228 offset:59136
	s_waitcnt lgkmcnt(8)
	v_mfma_f32_16x16x32_bf16 v[124:127], v[48:51], v[178:181], v[124:127]
	v_mfma_f32_16x16x32_bf16 v[128:131], v[52:55], v[178:181], v[128:131]
	v_mfma_f32_16x16x32_bf16 v[132:135], v[56:59], v[178:181], v[132:135]
	v_mfma_f32_16x16x32_bf16 v[136:139], v[60:63], v[178:181], v[136:139]
	ds_read_b64 v[48:49], v234
	ds_read_b64 v[50:51], v234
	ds_read_b64 v[52:53], v234 offset:8448
	ds_read_b64 v[54:55], v234 offset:8448
	ds_read_b64 v[56:57], v234 offset:16896
	ds_read_b64 v[58:59], v234 offset:16896
	ds_read_b64 v[60:61], v234 offset:25344
	s_waitcnt lgkmcnt(14)
	ds_read_b64 v[62:63], v234 offset:25344
	s_waitcnt lgkmcnt(8)
	v_mfma_f32_16x16x32_bf16 v[140:143], v[64:67], v[178:181], v[140:143]
	v_mfma_f32_16x16x32_bf16 v[144:147], v[68:71], v[178:181], v[144:147]
	v_mfma_f32_16x16x32_bf16 v[148:151], v[72:75], v[178:181], v[148:151]
	v_mfma_f32_16x16x32_bf16 v[152:155], v[76:79], v[178:181], v[152:155]
	ds_read_b64 v[64:65], v234 offset:33792
	ds_read_b64 v[66:67], v234 offset:33792
	ds_read_b64 v[68:69], v234 offset:42240
	ds_read_b64 v[70:71], v234 offset:42240
	ds_read_b64 v[72:73], v234 offset:50688
	ds_read_b64 v[74:75], v234 offset:50688
	ds_read_b64 v[76:77], v234 offset:59136
	s_waitcnt lgkmcnt(14)
; __device__ __forceinline__ unsigned pk2(float lo, float hi) { f32x2 v = {lo, hi}; bf2_t b = __builtin_convertvector(v, bf2_t); return __builtin_bit_cast(unsigned, b); }
; __device__ __forceinline__ void attn_phase(int wv, const Args& a, LAS unsigned char* lds, int w, bool dmy) {
;     ...
;         const float inv = 1.f / sum;
; #pragma unroll
;         for (int j = 0; j < 8; ++j) { u32x2 wv; wv.x = pk2(oacc[j][0] * inv, oacc[j][1] * inv); wv.y = pk2(oacc[j][2] * inv, oacc[j][3] * inv);
;             *(u32x2*)((dmy ? (bf16_t*)(a.ws + WS_DUMMY) + (size_t)qi * ATW : AQ + tokq * ATW) + head * 128 + j * 16 + 4 * fq) = wv; }
;         if (fq == 0) (dmy ? (float*)(a.ws + WS_DUMMY + MiB) + qi * 12 : LSE + tokq * 12)[head] = mx + __logf(sum);
	ds_read_b64 v[78:79], v234 offset:59136
	v_div_scale_f32 v80, s[2:3], v81, v81, 1.0
	v_div_scale_f32 v83, vcc, 1.0, v81, 1.0
	v_rcp_f32_e32 v82, v80
	s_nop 0
	v_fma_f32 v164, -v80, v82, 1.0
	v_fmac_f32_e32 v82, v164, v82
	v_mul_f32_e32 v103, v83, v82
	v_fma_f32 v164, -v80, v103, v83
	v_fmac_f32_e32 v103, v164, v82
	v_fma_f32 v80, -v80, v103, v83
	v_div_fmas_f32 v80, v80, v82, v103
	v_div_fixup_f32 v80, v80, v81, 1.0
	s_waitcnt lgkmcnt(8)
	v_mfma_f32_16x16x32_bf16 v[124:127], v[48:51], v[198:201], v[124:127]
	v_mfma_f32_16x16x32_bf16 v[128:131], v[52:55], v[198:201], v[128:131]
	v_mfma_f32_16x16x32_bf16 v[132:135], v[56:59], v[198:201], v[132:135]
	v_mfma_f32_16x16x32_bf16 v[136:139], v[60:63], v[198:201], v[136:139]
	s_waitcnt lgkmcnt(0)
	v_mfma_f32_16x16x32_bf16 v[140:143], v[64:67], v[198:201], v[140:143]
	v_mfma_f32_16x16x32_bf16 v[144:147], v[68:71], v[198:201], v[144:147]
	v_mfma_f32_16x16x32_bf16 v[148:151], v[72:75], v[198:201], v[148:151]
	v_mfma_f32_16x16x32_bf16 v[152:155], v[76:79], v[198:201], v[152:155]
	s_movk_i32 s2, 0xc00
	v_mov_b64_e32 v[82:83], s[78:79]
	v_mad_u64_u32 v[82:83], s[0:1], v102, s2, v[82:83]
	v_mov_b32_e32 v164, v83
	v_mov_b32_e32 v165, v189
	v_mad_u64_u32 v[164:165], s[0:1], v100, s2, v[164:165]
	s_lshl_b32 s0, s80, 7
	v_mov_b32_e32 v83, v164
	s_ashr_i32 s1, s0, 31
	v_lshl_add_u64 v[82:83], s[0:1], 1, v[82:83]
	v_lshlrev_b32_e32 v188, 1, v88
	s_nop 1
	v_lshl_add_u64 v[82:83], v[82:83], 0, v[188:189]
	v_and_b32_e32 v166, 8, v188
	v_mov_b32_e32 v167, 0
	v_lshl_add_u32 v166, v166, 1, v166
	v_lshl_add_u64 v[82:83], v[166:167], 0, v[82:83]
	v_mul_f32_e32 v124, v80, v124
	v_mul_f32_e32 v125, v80, v125
	v_mul_f32_e32 v126, v80, v126
	v_mul_f32_e32 v127, v80, v127
	v_mul_f32_e32 v128, v80, v128
	v_mul_f32_e32 v129, v80, v129
	v_mul_f32_e32 v130, v80, v130
	v_mul_f32_e32 v131, v80, v131
	v_mul_f32_e32 v132, v80, v132
	v_mul_f32_e32 v133, v80, v133
	v_mul_f32_e32 v134, v80, v134
	v_mul_f32_e32 v135, v80, v135
	v_mul_f32_e32 v136, v80, v136
	v_mul_f32_e32 v137, v80, v137
	v_mul_f32_e32 v138, v80, v138
	v_mul_f32_e32 v139, v80, v139
	v_mul_f32_e32 v140, v80, v140
	v_mul_f32_e32 v141, v80, v141
	v_mul_f32_e32 v142, v80, v142
	v_mul_f32_e32 v143, v80, v143
	v_mul_f32_e32 v144, v80, v144
	v_mul_f32_e32 v145, v80, v145
	v_mul_f32_e32 v146, v80, v146
	v_mul_f32_e32 v147, v80, v147
	v_mul_f32_e32 v148, v80, v148
	v_mul_f32_e32 v149, v80, v149
	v_mul_f32_e32 v150, v80, v150
	v_mul_f32_e32 v151, v80, v151
	v_mul_f32_e32 v152, v80, v152
	v_mul_f32_e32 v153, v80, v153
	v_mul_f32_e32 v154, v80, v154
	v_mul_f32_e32 v155, v80, v155
	v_cvt_pk_bf16_f32 v48, v124, v125
	v_cvt_pk_bf16_f32 v49, v126, v127
	v_cvt_pk_bf16_f32 v50, v128, v129
	v_cvt_pk_bf16_f32 v51, v130, v131
	v_cvt_pk_bf16_f32 v52, v132, v133
	v_cvt_pk_bf16_f32 v53, v134, v135
	v_cvt_pk_bf16_f32 v54, v136, v137
	v_cvt_pk_bf16_f32 v55, v138, v139
	v_cvt_pk_bf16_f32 v56, v140, v141
	v_cvt_pk_bf16_f32 v57, v142, v143
	v_cvt_pk_bf16_f32 v58, v144, v145
	v_cvt_pk_bf16_f32 v59, v146, v147
	v_cvt_pk_bf16_f32 v60, v148, v149
	v_cvt_pk_bf16_f32 v61, v150, v151
	v_cvt_pk_bf16_f32 v62, v152, v153
	v_cvt_pk_bf16_f32 v63, v154, v155
	s_nop 1
	v_permlane16_swap_b32_e32 v48, v50
	v_permlane16_swap_b32_e32 v49, v51
	v_permlane16_swap_b32_e32 v52, v54
	v_permlane16_swap_b32_e32 v53, v55
	v_permlane16_swap_b32_e32 v56, v58
	v_permlane16_swap_b32_e32 v57, v59
	v_permlane16_swap_b32_e32 v60, v62
	v_permlane16_swap_b32_e32 v61, v63
	global_store_dwordx4 v[82:83], v[48:51], off
	global_store_dwordx4 v[82:83], v[52:55], off offset:64
	global_store_dwordx4 v[82:83], v[56:59], off offset:128
	global_store_dwordx4 v[82:83], v[60:63], off offset:192
	s_mov_b64 s[86:87], exec
	v_readlane_b32 s0, v255, 3
	v_readlane_b32 s1, v255, 4
	s_and_b64 s[0:1], s[86:87], s[0:1]
	s_mov_b64 exec, s[0:1]
	s_cbranch_execz .LBB0_652
	v_cmp_gt_f32_e32 vcc, s33, v81
	v_readlane_b32 s0, v253, 38
	v_readlane_b32 s1, v253, 39
	v_cndmask_b32_e64 v48, 0, 32, vcc
	v_ldexp_f32 v48, v81, v48
	v_log_f32_e32 v48, v48
	v_cndmask_b32_e32 v49, 0, v237, vcc
	s_ashr_i32 s81, s80, 31
	v_mul_f32_e32 v50, 0x3f317217, v48
	v_fma_f32 v50, v48, s93, -v50
	v_fmac_f32_e32 v50, 0x3377d1cf, v48
	v_fmac_f32_e32 v50, 0x3f317217, v48
	v_cmp_lt_f32_e64 vcc, |v48|, s92
	s_nop 1
	v_cndmask_b32_e32 v48, v48, v50, vcc
	v_sub_f32_e32 v48, v48, v49
	v_add_f32_e32 v52, v101, v48
	v_mad_u64_u32 v[48:49], s[0:1], v102, 48, s[0:1]
	v_mov_b32_e32 v50, v49
	v_mad_u64_u32 v[50:51], s[0:1], v100, 48, v[50:51]
	v_mov_b32_e32 v49, v50
	v_lshl_add_u64 v[48:49], s[80:81], 2, v[48:49]
	global_store_dword v[48:49], v52, off
	s_branch .LBB0_652
